# local barriers: L1 invalidate issued at arrival (overlapping the arrival atomic and the wait for the other workgroups) instead of after release; otherwise as v59
# speedup vs baseline: 1.0244x; 1.0043x over previous
.LBB0_79:
	v_mov_b32_e32 v15, 0
	s_mov_b32 s1, 0xcd99adac
	s_lshr_b32 s1, s1, s21
	s_bitcmp1_b32 s1, 0
	s_cbranch_scc0 .Larr_done
	v_mov_b32_e32 v12, 0x23808
	ds_read_b32 v13, v12
	s_waitcnt lgkmcnt(0)
	v_readfirstlane_b32 s1, v13
	s_cmp_lg_u32 s1, 0
	s_cbranch_scc1 .Larr_have_flag
	v_mov_b32_e32 v14, 0x3600
	global_load_dwordx4 v[4:7], v14, s[24:25] sc1
	global_load_dwordx4 v[8:11], v14, s[24:25] offset:16 sc1
	s_waitcnt vmcnt(0)
	v_add_u32_e32 v13, -1, v4
	v_and_b32_e32 v16, v13, v4
	v_min_u32_e32 v14, v4, v5
	v_add_u32_e32 v13, -1, v5
	v_and_b32_e32 v13, v13, v5
	v_or_b32_e32 v16, v16, v13
	v_add_u32_e32 v13, -1, v6
	v_and_b32_e32 v13, v13, v6
	v_or_b32_e32 v16, v16, v13
	v_min_u32_e32 v14, v14, v6
	v_add_u32_e32 v13, -1, v7
	v_and_b32_e32 v13, v13, v7
	v_or_b32_e32 v16, v16, v13
	v_min_u32_e32 v14, v14, v7
	v_add_u32_e32 v13, -1, v8
	v_and_b32_e32 v13, v13, v8
	v_or_b32_e32 v16, v16, v13
	v_min_u32_e32 v14, v14, v8
	v_add_u32_e32 v13, -1, v9
	v_and_b32_e32 v13, v13, v9
	v_or_b32_e32 v16, v16, v13
	v_min_u32_e32 v14, v14, v9
	v_add_u32_e32 v13, -1, v10
	v_and_b32_e32 v13, v13, v10
	v_or_b32_e32 v16, v16, v13
	v_min_u32_e32 v14, v14, v10
	v_add_u32_e32 v13, -1, v11
	v_and_b32_e32 v13, v13, v11
	v_or_b32_e32 v16, v16, v13
	v_min_u32_e32 v14, v14, v11
	v_cmp_eq_u32_e32 vcc, 0, v16
	v_cmp_ne_u32_e64 s[10:11], 0, v14
	s_and_b64 s[10:11], s[10:11], vcc
	v_cndmask_b32_e64 v13, 2, 1, s[10:11]
	ds_write_b32 v12, v13
	s_nop 1
	v_readfirstlane_b32 s1, v13
.Larr_have_flag:
	s_cmp_eq_u32 s1, 1
	s_cbranch_scc0 .Larr_done
	v_mov_b32_e32 v15, 1

.LBB0_81:
	s_or_b64 exec, exec, s[6:7]
	v_readfirstlane_b32 s1, v15
	s_cmp_eq_u32 s1, 0
	s_cbranch_scc1 .Lno_early_inv
	buffer_inv sc1
.Lno_early_inv:
	v_cvt_f32_u32_e32 v4, v2
	s_waitcnt vmcnt(0)
	v_readfirstlane_b32 s1, v3
	v_sub_u32_e32 v3, 0, v2
	v_rcp_iflag_f32_e32 v4, v4
	v_add_u32_e32 v5, s1, v1
	v_mul_f32_e32 v4, 0x4f7ffffe, v4
	v_cvt_u32_f32_e32 v4, v4
	v_mul_lo_u32 v1, v3, v4
	v_mul_hi_u32 v1, v4, v1
	v_add_u32_e32 v1, v4, v1
	v_mul_hi_u32 v1, v5, v1
	v_mul_lo_u32 v3, v1, v2
	v_sub_u32_e32 v3, v5, v3
	v_add_u32_e32 v4, 1, v1
	v_cmp_ge_u32_e32 vcc, v3, v2
	s_nop 1
	v_cndmask_b32_e32 v1, v1, v4, vcc
	v_sub_u32_e32 v4, v3, v2
	v_cndmask_b32_e32 v3, v3, v4, vcc
	v_add_u32_e32 v4, 1, v1
	v_cmp_ge_u32_e32 vcc, v3, v2
	v_add_u32_e32 v3, 1, v5
	s_nop 0
	v_cndmask_b32_e32 v1, v1, v4, vcc
	v_mul_lo_u32 v4, v2, v1
	v_add_u32_e32 v2, v4, v2
	v_cmp_ne_u32_e32 vcc, v3, v2
	s_and_saveexec_b64 s[6:7], vcc
	s_xor_b64 s[6:7], exec, s[6:7]
	s_cbranch_execz .LBB0_95
	v_readlane_b32 s8, v252, 55
	v_readlane_b32 s9, v252, 56
	s_waitcnt lgkmcnt(0)
	s_nop 3
	global_load_dword v0, v169, s[8:9] sc1
	s_waitcnt vmcnt(0)
	v_cmp_eq_u32_e32 vcc, v0, v1
	s_and_saveexec_b64 s[8:9], vcc
	s_cbranch_execz .LBB0_94
	s_mov_b32 s1, 1
	s_mov_b64 s[10:11], 0
	s_branch .LBB0_85

.LBB0_94:
	s_or_b64 exec, exec, s[8:9]
	s_waitcnt vmcnt(0)
	v_readfirstlane_b32 s1, v15
	s_cmp_lg_u32 s1, 0
	s_cbranch_scc1 .Lskip_inv_nl
	buffer_inv sc1

.LBB0_95:
	s_andn2_saveexec_b64 s[6:7], s[6:7]
	s_cbranch_execz .LBB0_115
	s_mov_b64 s[6:7], exec
	v_readfirstlane_b32 s1, v15
	s_cmp_eq_u32 s1, 1
	s_cbranch_scc0 .Lbar_full
	s_branch .LBB0_112

.LBB0_112:
	s_or_b64 exec, exec, s[6:7]
	s_mov_b64 s[6:7], exec
	v_mbcnt_lo_u32_b32 v0, s6, 0
	v_mbcnt_hi_u32_b32 v0, s7, v0
	v_cmp_eq_u32_e32 vcc, 0, v0
	s_waitcnt vmcnt(0)
	v_readfirstlane_b32 s1, v15
	s_cmp_lg_u32 s1, 0
	s_cbranch_scc1 .Lskip_inv_ld
	buffer_inv sc1
.Lskip_inv_ld:
	s_and_saveexec_b64 s[8:9], vcc
	s_cbranch_execz .LBB0_114
	s_bcnt1_i32_b64 s1, s[6:7]
	v_readlane_b32 s6, v252, 55
	v_mov_b32_e32 v0, s1
	v_readlane_b32 s7, v252, 56
	s_nop 4
	global_atomic_add v169, v0, s[6:7]
